# LDS-DMA pieces spread to QK steps 0,2,4,6 (one global_load_lds per other MFMA pair) instead of steps 0-3
# speedup vs baseline: 1.0369x; 1.0115x over previous
; #define SBAR() __builtin_amdgcn_sched_barrier(0)
; __device__ __forceinline__ void qkt3(f32x16& p0, f32x16& p1, const bf16* Ks, const bf16x8* qr, int r32, int hi, const f32x16& cinit) {
;   { int cb = (hi * 8) * 2;
;     bf16x8 b0 = *reinterpret_cast<const bf16x8*>((const char*)Ks + KSWZ(r32, cb));
;     bf16x8 b1 = *reinterpret_cast<const bf16x8*>((const char*)Ks + KSWZ(32 + r32, cb));
;     p0 = __builtin_amdgcn_mfma_f32_32x32x16_bf16(b0, qr[0], cinit, 0, 0, 0);
;     p1 = __builtin_amdgcn_mfma_f32_32x32x16_bf16(b1, qr[0], cinit, 0, 0, 0); }
;   for (int d0 = 1; d0 < 8; ++d0) { int cb = (d0 * 16 + hi * 8) * 2;
;     bf16x8 b0 = *reinterpret_cast<const bf16x8*>((const char*)Ks + KSWZ(r32, cb));
;     bf16x8 b1 = *reinterpret_cast<const bf16x8*>((const char*)Ks + KSWZ(32 + r32, cb));
;     p0 = __builtin_amdgcn_mfma_f32_32x32x16_bf16(b0, qr[d0], p0, 0, 0, 0);
;     p1 = __builtin_amdgcn_mfma_f32_32x32x16_bf16(b1, qr[d0], p1, 0, 0, 0); }
; }
; __device__ __forceinline__ void attn_dense_body(const bf16* Qb, const bf16* __restrict__ Kh, const bf16* __restrict__ Vh, const bf16* __restrict__ Zb, ...
;     ...
;   for (int j = 1; j + 1 < NT; j += 2) {
;     SDMA(sN, (j + 1) * KVBLK);
;     SBAR(); qkt3(pB0, pB1, KSLOT(sC), qr, r32, hi, cinit);
;     finishSM4<16>(pA0, pA1, l_reg, pa0, pa1, pa2, pa3);
;     pv_d03(o, vb0 + sP * (int)SHM_V, pa0, pa1, pa2, pa3, pB0, pB1);
.LBB0_117:
	s_lshl_b32 s49, s48, 14
	s_mov_b32 s53, s46
	s_mov_b32 s46, s54
	s_add_i32 s86, s90, s49
	s_and_b32 s87, s47, 2
	s_lshl_b32 s87, s87, 14
	s_add_i32 s87, s87, s90
	s_lshl_b32 s15, s53, 14
	s_lshl_b32 s14, s54, 14
	v_add_u32_e32 v238, s15, v157
	ds_read_b128 v[246:249], v238 offset:49152
	ds_read_b128 v[238:241], v238 offset:57344
	v_add_u32_e32 v228, s15, v177
	ds_read_b128 v[224:227], v228 offset:49152
	ds_read_b128 v[228:231], v228 offset:57344
	v_cvt_pk_bf16_f32 v185, v202, v204
	v_cvt_pk_bf16_f32 v191, v180, v182
	v_cvt_pk_bf16_f32 v181, v212, v214
	v_cvt_pk_bf16_f32 v187, v220, v222
	v_cvt_pk_bf16_f32 v189, v158, v166
	s_waitcnt lgkmcnt(2)
	v_mfma_f32_32x32x16_bf16 v[96:111], v[246:249], v[140:143], v[64:79]
	v_mfma_f32_32x32x16_bf16 v[80:95], v[238:241], v[140:143], v[64:79]
	v_add_u32_e32 v238, s15, v175
	ds_read_b128 v[246:249], v238 offset:49152
	ds_read_b128 v[238:241], v238 offset:57344
	s_add_i32 m0, s86, 0xc000
	s_nop 0
	global_load_lds_dwordx4 v154, s[40:41]
	v_add_f32_e32 v162, 0, v179
	v_add_f32_e32 v162, v170, v162
	v_add_f32_e32 v162, v172, v162
	v_add_f32_e32 v162, v174, v162
	s_waitcnt lgkmcnt(2)
	v_mfma_f32_32x32x16_bf16 v[96:111], v[224:227], v[136:139], v[96:111]
	v_mfma_f32_32x32x16_bf16 v[80:95], v[228:231], v[136:139], v[80:95]
	v_add_u32_e32 v228, s15, v173
	ds_read_b128 v[224:227], v228 offset:49152
	ds_read_b128 v[228:231], v228 offset:57344
	v_add_f32_e32 v162, v184, v162
	v_add_f32_e32 v162, v186, v162
	v_add_f32_e32 v162, v188, v162
	v_add_f32_e32 v162, v190, v162
	s_waitcnt lgkmcnt(2)
	v_mfma_f32_32x32x16_bf16 v[96:111], v[246:249], v[132:135], v[96:111]
	v_mfma_f32_32x32x16_bf16 v[80:95], v[238:241], v[132:135], v[80:95]
	v_add_u32_e32 v238, s15, v171
	ds_read_b128 v[246:249], v238 offset:49152
	ds_read_b128 v[238:241], v238 offset:57344
	s_add_i32 m0, s86, 0xc400
	s_nop 0
	global_load_lds_dwordx4 v152, s[40:41]
	s_add_u32 s40, s40, 0x8000
	s_addc_u32 s41, s41, 0
	v_add_f32_e32 v162, v206, v162
	v_add_f32_e32 v162, v200, v162
	v_add_f32_e32 v162, v202, v162
	v_add_f32_e32 v162, v204, v162
	s_waitcnt lgkmcnt(2)
	v_mfma_f32_32x32x16_bf16 v[96:111], v[224:227], v[128:131], v[96:111]
	v_mfma_f32_32x32x16_bf16 v[80:95], v[228:231], v[128:131], v[80:95]
	v_add_u32_e32 v228, s15, v169
	ds_read_b128 v[224:227], v228 offset:49152
	ds_read_b128 v[228:231], v228 offset:57344
	v_add_f32_e32 v162, v216, v162
	v_add_f32_e32 v162, v218, v162
	v_add_f32_e32 v162, v220, v162
	v_add_f32_e32 v162, v222, v162
	s_waitcnt lgkmcnt(2)
	v_mfma_f32_32x32x16_bf16 v[96:111], v[246:249], v[124:127], v[96:111]
	v_mfma_f32_32x32x16_bf16 v[80:95], v[238:241], v[124:127], v[80:95]
	v_add_u32_e32 v238, s15, v167
	ds_read_b128 v[246:249], v238 offset:49152
	ds_read_b128 v[238:241], v238 offset:57344
	s_mov_b32 m0, s87
	s_nop 0
	global_load_lds_dwordx4 v150, s[84:85]
	v_add_f32_e32 v162, v168, v162
	v_add_f32_e32 v162, v156, v162
	v_add_f32_e32 v162, v158, v162
	v_add_f32_e32 v162, v166, v162
	s_waitcnt lgkmcnt(2)
	v_mfma_f32_32x32x16_bf16 v[96:111], v[224:227], v[120:123], v[96:111]
	v_mfma_f32_32x32x16_bf16 v[80:95], v[228:231], v[120:123], v[80:95]
	v_add_u32_e32 v228, s15, v159
	ds_read_b128 v[224:227], v228 offset:49152
	ds_read_b128 v[228:231], v228 offset:57344
	v_add_f32_e32 v162, v176, v162
	v_add_f32_e32 v162, v178, v162
	v_add_f32_e32 v162, v180, v162
	v_add_f32_e32 v162, v182, v162
	s_waitcnt lgkmcnt(2)
	v_mfma_f32_32x32x16_bf16 v[96:111], v[246:249], v[116:119], v[96:111]
	v_mfma_f32_32x32x16_bf16 v[80:95], v[238:241], v[116:119], v[80:95]
	s_add_i32 m0, s87, 0x400
	s_nop 0
	global_load_lds_dwordx4 v148, s[84:85]
	s_add_u32 s84, s84, 0x8000
	s_addc_u32 s85, s85, 0
	v_add_f32_e32 v162, v198, v162
	v_add_f32_e32 v162, v196, v162
	v_add_f32_e32 v162, v192, v162
	s_waitcnt lgkmcnt(0)
	v_mfma_f32_32x32x16_bf16 v[96:111], v[224:227], v[112:115], v[96:111]
	v_cvt_pk_bf16_f32 v238, v179, v170
	v_cvt_pk_bf16_f32 v179, v192, v194
	v_add_f32_e32 v162, v194, v162
	v_cvt_pk_bf16_f32 v241, v188, v190
	v_cvt_pk_bf16_f32 v190, v176, v178
	v_cvt_pk_bf16_f32 v178, v198, v196
	v_mfma_f32_32x32x16_bf16 v[80:95], v[228:231], v[112:115], v[80:95]
	s_bitcmp1_b32 s47, 1
	s_cselect_b32 s87, 0, 0x8000
	v_add_u32_e32 v246, s87, v147
	ds_read_b64_tr_b16 v[192:193], v246 offset:0
	ds_read_b64_tr_b16 v[194:195], v246 offset:0x100
	ds_read_b64_tr_b16 v[196:197], v246 offset:0x1000
	ds_read_b64_tr_b16 v[198:199], v246 offset:0x1100
	v_cvt_pk_bf16_f32 v240, v184, v186
	v_cvt_pk_bf16_f32 v184, v206, v200
	ds_read_b64_tr_b16 v[200:201], v246 offset:0x2000
	ds_read_b64_tr_b16 v[202:203], v246 offset:0x2100
	ds_read_b64_tr_b16 v[204:205], v246 offset:0x3000
	ds_read_b64_tr_b16 v[206:207], v246 offset:0x3100
	v_add_f32_e32 v162, v208, v162
	v_cvt_pk_bf16_f32 v180, v208, v210
	ds_read_b64_tr_b16 v[208:209], v246 offset:0x200
	v_add_f32_e32 v162, v210, v162
	ds_read_b64_tr_b16 v[210:211], v246 offset:0x300
	v_add_f32_e32 v162, v212, v162
	ds_read_b64_tr_b16 v[212:213], v246 offset:0x1200
	v_add_f32_e32 v162, v214, v162
	ds_read_b64_tr_b16 v[214:215], v246 offset:0x1300
	v_cvt_pk_bf16_f32 v186, v216, v218
	ds_read_b64_tr_b16 v[216:217], v246 offset:0x2200
	ds_read_b64_tr_b16 v[218:219], v246 offset:0x2300
	ds_read_b64_tr_b16 v[220:221], v246 offset:0x3200
	ds_read_b64_tr_b16 v[222:223], v246 offset:0x3300
	s_waitcnt lgkmcnt(8)
; #define SBAR() __builtin_amdgcn_sched_barrier(0)
; #define PV_RD2(D0, X) const s16x4 X##l0 = tr_read<v_rd_off2(D0, 0, 0)>(vb), X##h0 = tr_read<v_rd_off2(D0, 0, 1)>(vb), X##l1 = tr_read<v_rd_off2(D0, 1, 0)>(vb), X##h1 = tr_read<v_rd_off2(D0, 1, 1)>(vb), \
;                               X##l2 = tr_read<v_rd_off2(D0, 2, 0)>(vb), X##h2 = tr_read<v_rd_off2(D0, 2, 1)>(vb), X##l3 = tr_read<v_rd_off2(D0, 3, 0)>(vb), X##h3 = tr_read<v_rd_off2(D0, 3, 1)>(vb)
; #define EXP4(P, B) do { P[(B) + 0] = __builtin_amdgcn_exp2f(P[(B) + 0]); P[(B) + 1] = __builtin_amdgcn_exp2f(P[(B) + 1]); P[(B) + 2] = __builtin_amdgcn_exp2f(P[(B) + 2]); P[(B) + 3] = __builtin_amdgcn_exp2f(P[(B) + 3]); } while (0)
; #define DWAIT() asm volatile("s_waitcnt vmcnt(0)" ::: "memory")
; #define ROT() do { const int t_ = sP; sP = sC; sC = sN; sN = t_; } while (0)
; __device__ __forceinline__ void pv_d03(f32x16* o, int vb, bf16x8 pa0, bf16x8 pa1, bf16x8 pa2, bf16x8 pa3, f32x16& pn, f32x16& pm) {
;   PV_RD2(0, a);
;   PV_RD2(1, b); asm volatile("s_waitcnt lgkmcnt(8)" ::: "memory"); SBAR(); PV_MM2(o[0], a); EXP4(pn, 0); EXP4(pm, 0); SBAR();
;   PV_RD2(2, c); asm volatile("s_waitcnt lgkmcnt(8)" ::: "memory"); SBAR(); PV_MM2(o[1], b); EXP4(pn, 4); EXP4(pm, 4); SBAR();
;   PV_RD2(3, d); asm volatile("s_waitcnt lgkmcnt(8)" ::: "memory"); SBAR(); PV_MM2(o[2], c); EXP4(pn, 8); EXP4(pm, 8); SBAR();
;   asm volatile("s_waitcnt lgkmcnt(0)" ::: "memory"); SBAR(); PV_MM2(o[3], d); EXP4(pn, 12); EXP4(pm, 12);
; }
; __device__ __forceinline__ void attn_dense_body(const bf16* Qb, const bf16* __restrict__ Kh, const bf16* __restrict__ Vh, const bf16* __restrict__ Zb, ...
;     ...
;     pv_d03(o, vb0 + sP * (int)SHM_V, pa0, pa1, pa2, pa3, pB0, pB1);
;     DWAIT(); __syncthreads(); ROT();
;     SDMA(sN, (j + 2) * KVBLK);
;     SBAR(); qkt3(pA0, pA1, KSLOT(sC), qr, r32, hi, cinit);
	v_add_f32_e32 v146, v146, v162
	v_cvt_pk_bf16_f32 v188, v168, v156
	v_cvt_pk_bf16_f32 v239, v172, v174
	s_nop 1
	v_mfma_f32_32x32x16_bf16 v[48:63], v[192:195], v[238:241], v[48:63]
	v_exp_f32_e32 v156, v96
	v_exp_f32_e32 v158, v97
	v_exp_f32_e32 v166, v82
	v_exp_f32_e32 v168, v83
	v_exp_f32_e32 v162, v98
	v_exp_f32_e32 v163, v99
	v_exp_f32_e32 v164, v80
	v_mfma_f32_32x32x16_bf16 v[48:63], v[196:199], v[184:187], v[48:63]
	v_exp_f32_e32 v165, v81
	v_mfma_f32_32x32x16_bf16 v[48:63], v[200:203], v[188:191], v[48:63]
	v_mfma_f32_32x32x16_bf16 v[48:63], v[204:207], v[178:181], v[48:63]
	ds_read_b64_tr_b16 v[80:81], v246 offset:0x400
	ds_read_b64_tr_b16 v[82:83], v246 offset:0x500
	ds_read_b64_tr_b16 v[96:97], v246 offset:0x1400
	ds_read_b64_tr_b16 v[98:99], v246 offset:0x1500
	ds_read_b64_tr_b16 v[192:193], v246 offset:0x2400
	ds_read_b64_tr_b16 v[194:195], v246 offset:0x2500
	ds_read_b64_tr_b16 v[196:197], v246 offset:0x3400
	ds_read_b64_tr_b16 v[198:199], v246 offset:0x3500
	s_waitcnt lgkmcnt(8)
	v_mfma_f32_32x32x16_bf16 v[32:47], v[208:211], v[238:241], v[32:47]
	v_exp_f32_e32 v170, v100
	v_exp_f32_e32 v172, v101
	v_exp_f32_e32 v174, v102
	v_exp_f32_e32 v176, v103
	v_mfma_f32_32x32x16_bf16 v[32:47], v[212:215], v[184:187], v[32:47]
	v_mfma_f32_32x32x16_bf16 v[32:47], v[216:219], v[188:191], v[32:47]
	v_exp_f32_e32 v216, v84
	v_exp_f32_e32 v218, v86
	v_exp_f32_e32 v217, v85
	v_exp_f32_e32 v219, v87
	v_mfma_f32_32x32x16_bf16 v[32:47], v[220:223], v[178:181], v[32:47]
	ds_read_b64_tr_b16 v[84:85], v246 offset:0x600
	ds_read_b64_tr_b16 v[86:87], v246 offset:0x700
	ds_read_b64_tr_b16 v[100:101], v246 offset:0x1600
	ds_read_b64_tr_b16 v[102:103], v246 offset:0x1700
	ds_read_b64_tr_b16 v[200:201], v246 offset:0x2600
	ds_read_b64_tr_b16 v[202:203], v246 offset:0x2700
	ds_read_b64_tr_b16 v[204:205], v246 offset:0x3600
	ds_read_b64_tr_b16 v[206:207], v246 offset:0x3700
	s_waitcnt lgkmcnt(8)
	v_mfma_f32_32x32x16_bf16 v[16:31], v[80:83], v[238:241], v[16:31]
	v_exp_f32_e32 v220, v88
	v_exp_f32_e32 v222, v90
	v_exp_f32_e32 v221, v89
	v_exp_f32_e32 v223, v91
	v_mfma_f32_32x32x16_bf16 v[16:31], v[96:99], v[184:187], v[16:31]
	v_mfma_f32_32x32x16_bf16 v[16:31], v[192:195], v[188:191], v[16:31]
	v_exp_f32_e32 v192, v104
	v_exp_f32_e32 v194, v106
	v_exp_f32_e32 v193, v105
	v_exp_f32_e32 v195, v107
	v_mfma_f32_32x32x16_bf16 v[16:31], v[196:199], v[178:181], v[16:31]
	s_waitcnt lgkmcnt(0)
	s_waitcnt vmcnt(2)
	s_barrier
	s_add_i32 s86, s90, s14
	s_mov_b32 s87, 0x4000
	s_bitcmp1_b32 s47, 1
	s_cselect_b32 s87, 0x18000, s87
	s_add_i32 s87, s87, s90
	v_mfma_f32_32x32x16_bf16 v[0:15], v[84:87], v[238:241], v[0:15]
	v_exp_f32_e32 v196, v94
	v_mfma_f32_32x32x16_bf16 v[0:15], v[100:103], v[184:187], v[0:15]
	v_exp_f32_e32 v186, v108
	v_exp_f32_e32 v187, v109
	v_exp_f32_e32 v197, v95
	v_mfma_f32_32x32x16_bf16 v[0:15], v[200:203], v[188:191], v[0:15]
	v_exp_f32_e32 v188, v110
	v_exp_f32_e32 v190, v92
	v_exp_f32_e32 v189, v111
	v_exp_f32_e32 v191, v93
	v_mfma_f32_32x32x16_bf16 v[0:15], v[204:207], v[178:181], v[0:15]
	s_add_i32 s16, s49, 0
	v_add_u32_e32 v182, s16, v157
	ds_read_b128 v[178:181], v182 offset:49152
	ds_read_b128 v[182:185], v182 offset:57344
	v_add_u32_e32 v246, s16, v177
	ds_read_b128 v[238:241], v246 offset:49152
	ds_read_b128 v[246:249], v246 offset:57344
	s_mov_b32 s17, 0x18000
	s_bitcmp1_b32 s47, 1
	s_cselect_b32 s17, 0x4000, s17
	v_add_u32_e32 v206, s17, v147
	v_cvt_pk_bf16_f32 v214, v186, v187
	v_cvt_pk_bf16_f32 v215, v188, v189
	v_cvt_pk_bf16_f32 v230, v190, v191
	v_cvt_pk_bf16_f32 v212, v192, v193
	s_waitcnt lgkmcnt(2)
	v_mfma_f32_32x32x16_bf16 v[96:111], v[178:181], v[140:143], v[64:79]
	v_mfma_f32_32x32x16_bf16 v[80:95], v[182:185], v[140:143], v[64:79]
	v_add_u32_e32 v182, s16, v175
	ds_read_b128 v[178:181], v182 offset:49152
	ds_read_b128 v[182:185], v182 offset:57344
	s_add_i32 m0, s86, 0xc000
	s_nop 0
	global_load_lds_dwordx4 v154, s[40:41]
	v_cvt_pk_bf16_f32 v213, v194, v195
	v_cvt_pk_bf16_f32 v231, v196, v197
	v_cvt_pk_bf16_f32 v226, v216, v217
	s_waitcnt lgkmcnt(2)
	v_mfma_f32_32x32x16_bf16 v[96:111], v[238:241], v[136:139], v[96:111]
	v_mfma_f32_32x32x16_bf16 v[80:95], v[246:249], v[136:139], v[80:95]
	v_add_u32_e32 v246, s16, v173
	ds_read_b128 v[238:241], v246 offset:49152
	ds_read_b128 v[246:249], v246 offset:57344
	v_cvt_pk_bf16_f32 v227, v218, v219
	v_cvt_pk_bf16_f32 v208, v156, v158
	v_cvt_pk_bf16_f32 v210, v170, v172
	s_waitcnt lgkmcnt(2)
	v_mfma_f32_32x32x16_bf16 v[96:111], v[178:181], v[132:135], v[96:111]
	v_mfma_f32_32x32x16_bf16 v[80:95], v[182:185], v[132:135], v[80:95]
	v_add_u32_e32 v182, s16, v171
	ds_read_b128 v[178:181], v182 offset:49152
	ds_read_b128 v[182:185], v182 offset:57344
	s_add_i32 m0, s86, 0xc400
	s_nop 0
	global_load_lds_dwordx4 v152, s[40:41]
	s_add_u32 s40, s40, 0x8000
	s_addc_u32 s41, s41, 0
	v_cvt_pk_bf16_f32 v209, v162, v163
	v_cvt_pk_bf16_f32 v211, v174, v176
	v_cvt_pk_bf16_f32 v224, v164, v165
	s_waitcnt lgkmcnt(2)
	v_mfma_f32_32x32x16_bf16 v[96:111], v[238:241], v[128:131], v[96:111]
	v_mfma_f32_32x32x16_bf16 v[80:95], v[246:249], v[128:131], v[80:95]
	v_add_u32_e32 v246, s16, v169
	ds_read_b128 v[238:241], v246 offset:49152
	ds_read_b128 v[246:249], v246 offset:57344
	v_cvt_pk_bf16_f32 v225, v166, v168
	v_cvt_pk_bf16_f32 v228, v220, v221
	v_cvt_pk_bf16_f32 v229, v222, v223
	s_waitcnt lgkmcnt(2)
	v_mfma_f32_32x32x16_bf16 v[96:111], v[178:181], v[124:127], v[96:111]
	v_mfma_f32_32x32x16_bf16 v[80:95], v[182:185], v[124:127], v[80:95]
	v_add_u32_e32 v182, s16, v167
	ds_read_b128 v[178:181], v182 offset:49152
	ds_read_b128 v[182:185], v182 offset:57344
	s_mov_b32 m0, s87
	s_nop 0
	global_load_lds_dwordx4 v150, s[84:85]
	s_waitcnt lgkmcnt(2)
; #define SBAR() __builtin_amdgcn_sched_barrier(0)
; #define PV_RD2(D0, X) const s16x4 X##l0 = tr_read<v_rd_off2(D0, 0, 0)>(vb), X##h0 = tr_read<v_rd_off2(D0, 0, 1)>(vb), X##l1 = tr_read<v_rd_off2(D0, 1, 0)>(vb), X##h1 = tr_read<v_rd_off2(D0, 1, 1)>(vb), \
;                               X##l2 = tr_read<v_rd_off2(D0, 2, 0)>(vb), X##h2 = tr_read<v_rd_off2(D0, 2, 1)>(vb), X##l3 = tr_read<v_rd_off2(D0, 3, 0)>(vb), X##h3 = tr_read<v_rd_off2(D0, 3, 1)>(vb)
; #define EXP4(P, B) do { P[(B) + 0] = __builtin_amdgcn_exp2f(P[(B) + 0]); P[(B) + 1] = __builtin_amdgcn_exp2f(P[(B) + 1]); P[(B) + 2] = __builtin_amdgcn_exp2f(P[(B) + 2]); P[(B) + 3] = __builtin_amdgcn_exp2f(P[(B) + 3]); } while (0)
; #define DWAIT() asm volatile("s_waitcnt vmcnt(0)" ::: "memory")
; #define ROT() do { const int t_ = sP; sP = sC; sC = sN; sN = t_; } while (0)
; __device__ __forceinline__ void pv_d03(f32x16* o, int vb, bf16x8 pa0, bf16x8 pa1, bf16x8 pa2, bf16x8 pa3, f32x16& pn, f32x16& pm) {
;   PV_RD2(0, a);
;   PV_RD2(1, b); asm volatile("s_waitcnt lgkmcnt(8)" ::: "memory"); SBAR(); PV_MM2(o[0], a); EXP4(pn, 0); EXP4(pm, 0); SBAR();
;   PV_RD2(2, c); asm volatile("s_waitcnt lgkmcnt(8)" ::: "memory"); SBAR(); PV_MM2(o[1], b); EXP4(pn, 4); EXP4(pm, 4); SBAR();
;   PV_RD2(3, d); asm volatile("s_waitcnt lgkmcnt(8)" ::: "memory"); SBAR(); PV_MM2(o[2], c); EXP4(pn, 8); EXP4(pm, 8); SBAR();
;   asm volatile("s_waitcnt lgkmcnt(0)" ::: "memory"); SBAR(); PV_MM2(o[3], d); EXP4(pn, 12); EXP4(pm, 12);
; }
; __device__ __forceinline__ void attn_dense_body(const bf16* Qb, const bf16* __restrict__ Kh, const bf16* __restrict__ Vh, const bf16* __restrict__ Zb, ...
;     ...
;     SBAR(); qkt3(pA0, pA1, KSLOT(sC), qr, r32, hi, cinit);
;     finishSM4<16>(pB0, pB1, l_reg, pa0, pa1, pa2, pa3);
;     pv_d03(o, vb0 + sP * (int)SHM_V, pa0, pa1, pa2, pa3, pA0, pA1);
;     DWAIT(); __syncthreads(); ROT();
	v_mfma_f32_32x32x16_bf16 v[96:111], v[238:241], v[120:123], v[96:111]
	v_mfma_f32_32x32x16_bf16 v[80:95], v[246:249], v[120:123], v[80:95]
	v_add_u32_e32 v246, s16, v159
	ds_read_b128 v[238:241], v246 offset:49152
	ds_read_b128 v[246:249], v246 offset:57344
	s_waitcnt lgkmcnt(2)
	v_mfma_f32_32x32x16_bf16 v[96:111], v[178:181], v[116:119], v[96:111]
	v_mfma_f32_32x32x16_bf16 v[80:95], v[182:185], v[116:119], v[80:95]
	s_add_i32 m0, s87, 0x400
	s_nop 0
	global_load_lds_dwordx4 v148, s[84:85]
	s_add_u32 s84, s84, 0x8000
	s_addc_u32 s85, s85, 0
	v_add_f32_e32 v178, 0, v156
	v_add_f32_e32 v178, v158, v178
	v_add_f32_e32 v178, v162, v178
	v_add_f32_e32 v178, v163, v178
	v_add_f32_e32 v178, v170, v178
	v_add_f32_e32 v178, v172, v178
	v_add_f32_e32 v178, v174, v178
	v_add_f32_e32 v178, v176, v178
	v_add_f32_e32 v178, v192, v178
	v_add_f32_e32 v178, v193, v178
	v_add_f32_e32 v178, v194, v178
	v_add_f32_e32 v178, v195, v178
	v_add_f32_e32 v178, v186, v178
	v_add_f32_e32 v178, v187, v178
	v_add_f32_e32 v178, v188, v178
	v_add_f32_e32 v178, v189, v178
	s_waitcnt lgkmcnt(0)
	v_mfma_f32_32x32x16_bf16 v[96:111], v[238:241], v[112:115], v[96:111]
	v_add_f32_e32 v178, v164, v178
	v_add_f32_e32 v178, v165, v178
	v_add_f32_e32 v178, v166, v178
	v_add_f32_e32 v178, v168, v178
	v_add_f32_e32 v178, v216, v178
	v_add_f32_e32 v178, v217, v178
	v_add_f32_e32 v178, v218, v178
	v_add_f32_e32 v178, v219, v178
	v_add_f32_e32 v178, v220, v178
	v_add_f32_e32 v178, v221, v178
	v_add_f32_e32 v178, v222, v178
	v_add_f32_e32 v178, v223, v178
	v_add_f32_e32 v178, v190, v178
	v_add_f32_e32 v178, v191, v178
	v_add_f32_e32 v178, v196, v178
	v_add_f32_e32 v178, v197, v178
	v_add_f32_e32 v146, v146, v178
	ds_read_b64_tr_b16 v[178:179], v206 offset:0
	ds_read_b64_tr_b16 v[180:181], v206 offset:0x100
	v_mfma_f32_32x32x16_bf16 v[80:95], v[246:249], v[112:115], v[80:95]
	ds_read_b64_tr_b16 v[182:183], v206 offset:0x1000
	ds_read_b64_tr_b16 v[184:185], v206 offset:0x1100
	ds_read_b64_tr_b16 v[186:187], v206 offset:0x2000
	ds_read_b64_tr_b16 v[188:189], v206 offset:0x2100
	ds_read_b64_tr_b16 v[190:191], v206 offset:0x3000
	ds_read_b64_tr_b16 v[192:193], v206 offset:0x3100
	ds_read_b64_tr_b16 v[194:195], v206 offset:0x200
	ds_read_b64_tr_b16 v[196:197], v206 offset:0x300
	ds_read_b64_tr_b16 v[198:199], v206 offset:0x1200
	ds_read_b64_tr_b16 v[200:201], v206 offset:0x1300
	ds_read_b64_tr_b16 v[202:203], v206 offset:0x2200
	ds_read_b64_tr_b16 v[204:205], v206 offset:0x2300
	ds_read_b64_tr_b16 v[216:217], v206 offset:0x3200
	ds_read_b64_tr_b16 v[218:219], v206 offset:0x3300
	s_waitcnt lgkmcnt(8)
	v_mfma_f32_32x32x16_bf16 v[48:63], v[178:181], v[208:211], v[48:63]
	v_exp_f32_e32 v179, v96
	v_exp_f32_e32 v170, v97
	v_exp_f32_e32 v172, v98
	v_exp_f32_e32 v174, v99
	s_nop 6
	v_exp_f32_e32 v168, v80
	v_exp_f32_e32 v156, v81
	v_exp_f32_e32 v158, v82
	v_mfma_f32_32x32x16_bf16 v[48:63], v[182:185], v[212:215], v[48:63]
	v_exp_f32_e32 v166, v83
	v_mfma_f32_32x32x16_bf16 v[48:63], v[186:189], v[224:227], v[48:63]
	v_mfma_f32_32x32x16_bf16 v[48:63], v[190:193], v[228:231], v[48:63]
	ds_read_b64_tr_b16 v[80:81], v206 offset:0x400
	ds_read_b64_tr_b16 v[82:83], v206 offset:0x500
	ds_read_b64_tr_b16 v[96:97], v206 offset:0x1400
	ds_read_b64_tr_b16 v[98:99], v206 offset:0x1500
	ds_read_b64_tr_b16 v[220:221], v206 offset:0x2400
	ds_read_b64_tr_b16 v[222:223], v206 offset:0x2500
	ds_read_b64_tr_b16 v[238:239], v206 offset:0x3400
	ds_read_b64_tr_b16 v[240:241], v206 offset:0x3500
	s_waitcnt lgkmcnt(8)
	v_mfma_f32_32x32x16_bf16 v[32:47], v[194:197], v[208:211], v[32:47]
	v_exp_f32_e32 v184, v100
	v_exp_f32_e32 v186, v101
	v_exp_f32_e32 v188, v102
	v_exp_f32_e32 v190, v103
	v_exp_f32_e32 v176, v84
	v_exp_f32_e32 v178, v85
	v_exp_f32_e32 v180, v86
	v_mfma_f32_32x32x16_bf16 v[32:47], v[198:201], v[212:215], v[32:47]
	v_exp_f32_e32 v182, v87
	v_mfma_f32_32x32x16_bf16 v[32:47], v[202:205], v[224:227], v[32:47]
	v_mfma_f32_32x32x16_bf16 v[32:47], v[216:219], v[228:231], v[32:47]
	ds_read_b64_tr_b16 v[84:85], v206 offset:0x600
	ds_read_b64_tr_b16 v[86:87], v206 offset:0x700
	ds_read_b64_tr_b16 v[100:101], v206 offset:0x1600
	ds_read_b64_tr_b16 v[102:103], v206 offset:0x1700
	ds_read_b64_tr_b16 v[248:249], v206 offset:0x2600
	ds_read_b64_tr_b16 v[250:251], v206 offset:0x2700
	ds_read_b64_tr_b16 v[162:163], v206 offset:0x3600
	ds_read_b64_tr_b16 v[164:165], v206 offset:0x3700
	s_waitcnt lgkmcnt(8)
	v_mfma_f32_32x32x16_bf16 v[16:31], v[80:83], v[208:211], v[16:31]
	v_exp_f32_e32 v206, v104
	v_exp_f32_e32 v200, v105
	v_exp_f32_e32 v202, v106
	v_exp_f32_e32 v204, v107
	v_exp_f32_e32 v198, v88
	v_exp_f32_e32 v196, v89
	v_exp_f32_e32 v192, v90
	v_mfma_f32_32x32x16_bf16 v[16:31], v[96:99], v[212:215], v[16:31]
	v_exp_f32_e32 v194, v91
	v_mfma_f32_32x32x16_bf16 v[16:31], v[220:223], v[224:227], v[16:31]
	v_mfma_f32_32x32x16_bf16 v[16:31], v[238:241], v[228:231], v[16:31]
	s_waitcnt lgkmcnt(0)
	v_mfma_f32_32x32x16_bf16 v[0:15], v[84:87], v[208:211], v[0:15]
	v_exp_f32_e32 v216, v108
	v_exp_f32_e32 v218, v109
	v_exp_f32_e32 v220, v110
	v_exp_f32_e32 v222, v111
	v_exp_f32_e32 v208, v92
	v_exp_f32_e32 v210, v93
	v_mfma_f32_32x32x16_bf16 v[0:15], v[100:103], v[212:215], v[0:15]
	v_exp_f32_e32 v212, v94
	v_exp_f32_e32 v214, v95
	s_add_i32 s47, s47, 2
	s_mov_b32 s54, s48
	s_mov_b32 s48, s53
	v_mfma_f32_32x32x16_bf16 v[0:15], v[248:251], v[224:227], v[0:15]
	s_waitcnt vmcnt(2)
	s_barrier
	s_cmp_lt_u32 s47, s52
	v_mfma_f32_32x32x16_bf16 v[0:15], v[162:165], v[228:231], v[0:15]
	s_cbranch_scc1 .LBB0_117
; #define SBAR() __builtin_amdgcn_sched_barrier(0)
; #define PV_RD2(D0, X) const s16x4 X##l0 = tr_read<v_rd_off2(D0, 0, 0)>(vb), X##h0 = tr_read<v_rd_off2(D0, 0, 1)>(vb), X##l1 = tr_read<v_rd_off2(D0, 1, 0)>(vb), X##h1 = tr_read<v_rd_off2(D0, 1, 1)>(vb), \
;                               X##l2 = tr_read<v_rd_off2(D0, 2, 0)>(vb), X##h2 = tr_read<v_rd_off2(D0, 2, 1)>(vb), X##l3 = tr_read<v_rd_off2(D0, 3, 0)>(vb), X##h3 = tr_read<v_rd_off2(D0, 3, 1)>(vb)
; #define EXP4(P, B) do { P[(B) + 0] = __builtin_amdgcn_exp2f(P[(B) + 0]); P[(B) + 1] = __builtin_amdgcn_exp2f(P[(B) + 1]); P[(B) + 2] = __builtin_amdgcn_exp2f(P[(B) + 2]); P[(B) + 3] = __builtin_amdgcn_exp2f(P[(B) + 3]); } while (0)
; __device__ __forceinline__ void qkt3(f32x16& p0, f32x16& p1, const bf16* Ks, const bf16x8* qr, int r32, int hi, const f32x16& cinit) {
;   { int cb = (hi * 8) * 2;
;     bf16x8 b0 = *reinterpret_cast<const bf16x8*>((const char*)Ks + KSWZ(r32, cb));
;     bf16x8 b1 = *reinterpret_cast<const bf16x8*>((const char*)Ks + KSWZ(32 + r32, cb));
;     p0 = __builtin_amdgcn_mfma_f32_32x32x16_bf16(b0, qr[0], cinit, 0, 0, 0);
;     p1 = __builtin_amdgcn_mfma_f32_32x32x16_bf16(b1, qr[0], cinit, 0, 0, 0); }
;   for (int d0 = 1; d0 < 8; ++d0) { int cb = (d0 * 16 + hi * 8) * 2;
;     bf16x8 b0 = *reinterpret_cast<const bf16x8*>((const char*)Ks + KSWZ(r32, cb));
;     bf16x8 b1 = *reinterpret_cast<const bf16x8*>((const char*)Ks + KSWZ(32 + r32, cb));
;     p0 = __builtin_amdgcn_mfma_f32_32x32x16_bf16(b0, qr[d0], p0, 0, 0, 0);
;     p1 = __builtin_amdgcn_mfma_f32_32x32x16_bf16(b1, qr[d0], p1, 0, 0, 0); }
; }
; __device__ __forceinline__ void pv_d03(f32x16* o, int vb, bf16x8 pa0, bf16x8 pa1, bf16x8 pa2, bf16x8 pa3, f32x16& pn, f32x16& pm) {
;   PV_RD2(0, a);
;   PV_RD2(1, b); asm volatile("s_waitcnt lgkmcnt(8)" ::: "memory"); SBAR(); PV_MM2(o[0], a); EXP4(pn, 0); EXP4(pm, 0); SBAR();
;   PV_RD2(2, c); asm volatile("s_waitcnt lgkmcnt(8)" ::: "memory"); SBAR(); PV_MM2(o[1], b); EXP4(pn, 4); EXP4(pm, 4); SBAR();
;   PV_RD2(3, d); asm volatile("s_waitcnt lgkmcnt(8)" ::: "memory"); SBAR(); PV_MM2(o[2], c); EXP4(pn, 8); EXP4(pm, 8); SBAR();
;   asm volatile("s_waitcnt lgkmcnt(0)" ::: "memory"); SBAR(); PV_MM2(o[3], d); EXP4(pn, 12); EXP4(pm, 12);
; }
	s_add_u32 s40, s36, s44
	s_addc_u32 s41, s50, s45
	s_add_i32 s14, s14, 0
	v_add_u32_e32 v100, s14, v157
	ds_read_b128 v[96:99], v100 offset:49152
	v_add_u32_e32 v104, s14, v159
	v_add_f32_e32 v148, 0, v179
	v_cvt_pk_bf16_f32 v108, v179, v170
	v_cvt_pk_bf16_f32 v109, v172, v174
	v_cvt_pk_bf16_f32 v110, v184, v186
	v_cvt_pk_bf16_f32 v111, v188, v190
	s_waitcnt lgkmcnt(0)
	v_mfma_f32_32x32x16_bf16 v[80:95], v[96:99], v[140:143], v[64:79]
	ds_read_b128 v[96:99], v100 offset:57344
	v_add_u32_e32 v100, s14, v177
	s_waitcnt lgkmcnt(0)
	v_mfma_f32_32x32x16_bf16 v[64:79], v[96:99], v[140:143], v[64:79]
	ds_read_b128 v[96:99], v100 offset:49152
	s_waitcnt lgkmcnt(0)
	v_mfma_f32_32x32x16_bf16 v[80:95], v[96:99], v[136:139], v[80:95]
	ds_read_b128 v[96:99], v100 offset:57344
	v_add_u32_e32 v100, s14, v175
	s_waitcnt lgkmcnt(0)
	v_mfma_f32_32x32x16_bf16 v[64:79], v[96:99], v[136:139], v[64:79]
	ds_read_b128 v[96:99], v100 offset:49152
	s_waitcnt lgkmcnt(0)
	v_mfma_f32_32x32x16_bf16 v[80:95], v[96:99], v[132:135], v[80:95]
	ds_read_b128 v[96:99], v100 offset:57344
	v_add_u32_e32 v100, s14, v173
	s_waitcnt lgkmcnt(0)
	v_mfma_f32_32x32x16_bf16 v[64:79], v[96:99], v[132:135], v[64:79]
	ds_read_b128 v[96:99], v100 offset:49152
	s_waitcnt lgkmcnt(0)
	v_mfma_f32_32x32x16_bf16 v[80:95], v[96:99], v[128:131], v[80:95]
	ds_read_b128 v[96:99], v100 offset:57344
	v_add_u32_e32 v100, s14, v171
	s_waitcnt lgkmcnt(0)
	v_mfma_f32_32x32x16_bf16 v[64:79], v[96:99], v[128:131], v[64:79]
	ds_read_b128 v[96:99], v100 offset:49152
	s_waitcnt lgkmcnt(0)
	v_mfma_f32_32x32x16_bf16 v[80:95], v[96:99], v[124:127], v[80:95]
	ds_read_b128 v[96:99], v100 offset:57344
	v_add_u32_e32 v100, s14, v169
	s_waitcnt lgkmcnt(0)
	v_mfma_f32_32x32x16_bf16 v[64:79], v[96:99], v[124:127], v[64:79]
	ds_read_b128 v[96:99], v100 offset:49152
	s_waitcnt lgkmcnt(0)
	v_mfma_f32_32x32x16_bf16 v[80:95], v[96:99], v[120:123], v[80:95]
	ds_read_b128 v[96:99], v100 offset:57344
	v_add_u32_e32 v100, s14, v167
	s_waitcnt lgkmcnt(0)
	v_mfma_f32_32x32x16_bf16 v[64:79], v[96:99], v[120:123], v[64:79]
	ds_read_b128 v[96:99], v100 offset:49152
	s_waitcnt lgkmcnt(0)
	v_mfma_f32_32x32x16_bf16 v[80:95], v[96:99], v[116:119], v[80:95]
	ds_read_b128 v[96:99], v100 offset:57344
	ds_read_b128 v[100:103], v104 offset:49152
	ds_read_b128 v[104:107], v104 offset:57344
	s_waitcnt lgkmcnt(2)
	v_mfma_f32_32x32x16_bf16 v[64:79], v[96:99], v[116:119], v[64:79]
	v_cvt_pk_bf16_f32 v96, v206, v200
	v_cvt_pk_bf16_f32 v97, v202, v204
	v_cvt_pk_bf16_f32 v98, v216, v218
	v_cvt_pk_bf16_f32 v99, v220, v222
	v_cvt_pk_bf16_f32 v116, v198, v196
	v_cvt_pk_bf16_f32 v117, v192, v194
	v_cvt_pk_bf16_f32 v118, v208, v210
	s_waitcnt lgkmcnt(1)
	v_mfma_f32_32x32x16_bf16 v[80:95], v[100:103], v[112:115], v[80:95]
	v_cvt_pk_bf16_f32 v100, v168, v156
	v_cvt_pk_bf16_f32 v101, v158, v166
	v_cvt_pk_bf16_f32 v102, v176, v178
	v_cvt_pk_bf16_f32 v103, v180, v182
	v_cvt_pk_bf16_f32 v119, v212, v214
	s_waitcnt lgkmcnt(0)
	v_mfma_f32_32x32x16_bf16 v[64:79], v[104:107], v[112:115], v[64:79]
	s_mov_b32 s87, 0x18000
	s_bitcmp1_b32 s52, 1
	s_cselect_b32 s87, 0x4000, s87
	v_add_u32_e32 v246, s87, v147
	s_bitcmp1_b32 s52, 1
	s_cselect_b32 s87, 0, 0x8000
	v_add_u32_e32 v147, s87, v147
	ds_read_b64_tr_b16 v[104:105], v147 offset:0
	ds_read_b64_tr_b16 v[106:107], v147 offset:0x100
	ds_read_b64_tr_b16 v[112:113], v147 offset:0x1000
	ds_read_b64_tr_b16 v[114:115], v147 offset:0x1100
	ds_read_b64_tr_b16 v[120:121], v147 offset:0x2000
	ds_read_b64_tr_b16 v[122:123], v147 offset:0x2100
	ds_read_b64_tr_b16 v[124:125], v147 offset:0x3000
	ds_read_b64_tr_b16 v[126:127], v147 offset:0x3100
	ds_read_b64_tr_b16 v[128:129], v147 offset:0x200
	ds_read_b64_tr_b16 v[130:131], v147 offset:0x300
	ds_read_b64_tr_b16 v[132:133], v147 offset:0x1200
	ds_read_b64_tr_b16 v[134:135], v147 offset:0x1300
	ds_read_b64_tr_b16 v[136:137], v147 offset:0x2200
	ds_read_b64_tr_b16 v[138:139], v147 offset:0x2300
	ds_read_b64_tr_b16 v[140:141], v147 offset:0x3200
	ds_read_b64_tr_b16 v[142:143], v147 offset:0x3300
	s_waitcnt lgkmcnt(8)
	s_nop 0
	v_mfma_f32_32x32x16_bf16 v[48:63], v[104:107], v[108:111], v[48:63]
	s_nop 1
	v_exp_f32_e32 v171, v80
	v_exp_f32_e32 v173, v81
	v_exp_f32_e32 v175, v82
	v_exp_f32_e32 v185, v83
	s_nop 2
	v_exp_f32_e32 v157, v64
	v_exp_f32_e32 v159, v65
	v_exp_f32_e32 v167, v66
	v_mfma_f32_32x32x16_bf16 v[48:63], v[112:115], v[96:99], v[48:63]
	v_exp_f32_e32 v177, v67
	v_mfma_f32_32x32x16_bf16 v[48:63], v[120:123], v[100:103], v[48:63]
	v_mfma_f32_32x32x16_bf16 v[48:63], v[124:127], v[116:119], v[48:63]
	ds_read_b64_tr_b16 v[64:65], v147 offset:0x400
	ds_read_b64_tr_b16 v[66:67], v147 offset:0x500
	ds_read_b64_tr_b16 v[80:81], v147 offset:0x1400
	ds_read_b64_tr_b16 v[82:83], v147 offset:0x1500
	ds_read_b64_tr_b16 v[104:105], v147 offset:0x2400
	ds_read_b64_tr_b16 v[106:107], v147 offset:0x2500
	ds_read_b64_tr_b16 v[112:113], v147 offset:0x3400
	ds_read_b64_tr_b16 v[114:115], v147 offset:0x3500
	s_waitcnt lgkmcnt(8)
	v_mfma_f32_32x32x16_bf16 v[32:47], v[128:131], v[108:111], v[32:47]
	v_exp_f32_e32 v187, v84
	v_exp_f32_e32 v189, v85
	v_exp_f32_e32 v191, v86
	v_exp_f32_e32 v207, v87
	v_exp_f32_e32 v179, v68
	v_exp_f32_e32 v181, v69
	v_exp_f32_e32 v183, v70
	v_mfma_f32_32x32x16_bf16 v[32:47], v[132:135], v[96:99], v[32:47]
	v_exp_f32_e32 v199, v71
	v_mfma_f32_32x32x16_bf16 v[32:47], v[136:139], v[100:103], v[32:47]
	v_mfma_f32_32x32x16_bf16 v[32:47], v[140:143], v[116:119], v[32:47]
	ds_read_b64_tr_b16 v[68:69], v147 offset:0x600
	ds_read_b64_tr_b16 v[70:71], v147 offset:0x700
	ds_read_b64_tr_b16 v[84:85], v147 offset:0x1600
	ds_read_b64_tr_b16 v[86:87], v147 offset:0x1700
	ds_read_b64_tr_b16 v[120:121], v147 offset:0x2600
	ds_read_b64_tr_b16 v[122:123], v147 offset:0x2700
	ds_read_b64_tr_b16 v[124:125], v147 offset:0x3600
	ds_read_b64_tr_b16 v[126:127], v147 offset:0x3700
	s_waitcnt lgkmcnt(8)
; #define SBAR() __builtin_amdgcn_sched_barrier(0)
; #define PK8(P, BASE, OUT) do { u32x4 w = {cvtpk(P[BASE + 0], P[BASE + 1]), cvtpk(P[BASE + 2], P[BASE + 3]), cvtpk(P[BASE + 4], P[BASE + 5]), cvtpk(P[BASE + 6], P[BASE + 7])}; OUT = *reinterpret_cast<bf16x8*>(&w); } while (0)
; #define PV_RD2(D0, X) const s16x4 X##l0 = tr_read<v_rd_off2(D0, 0, 0)>(vb), X##h0 = tr_read<v_rd_off2(D0, 0, 1)>(vb), X##l1 = tr_read<v_rd_off2(D0, 1, 0)>(vb), X##h1 = tr_read<v_rd_off2(D0, 1, 1)>(vb), \
;                               X##l2 = tr_read<v_rd_off2(D0, 2, 0)>(vb), X##h2 = tr_read<v_rd_off2(D0, 2, 1)>(vb), X##l3 = tr_read<v_rd_off2(D0, 3, 0)>(vb), X##h3 = tr_read<v_rd_off2(D0, 3, 1)>(vb)
; template <int FIRST> __device__ __forceinline__ void finishSM4(f32x16& p0, f32x16& p1, float& l_reg, bf16x8& pa0, bf16x8& pa1, bf16x8& pa2, bf16x8& pa3) {
;   for (int r = FIRST; r < 16; ++r) p1[r] = __builtin_amdgcn_exp2f(p1[r]);
;   float ps = 0; for (int r = 0; r < 16; ++r) ps += p0[r]; for (int r = 0; r < 16; ++r) ps += p1[r];
;   l_reg += ps;
;     ...
;   PK8(p0, 0, pa0); PK8(p0, 8, pa1); PK8(p1, 0, pa2); PK8(p1, 8, pa3);
;     ...
; }
; __device__ __forceinline__ void pv_d02(f32x16* o, int vb, bf16x8 pa0, bf16x8 pa1, bf16x8 pa2, bf16x8 pa3) {
;   PV_RD2(0, a);
;   PV_RD2(1, b); asm volatile("s_waitcnt lgkmcnt(8)" ::: "memory"); SBAR(); PV_MM2(o[0], a); SBAR();
;   PV_RD2(2, c); asm volatile("s_waitcnt lgkmcnt(8)" ::: "memory"); SBAR(); PV_MM2(o[1], b); SBAR();
;   PV_RD2(3, d); asm volatile("s_waitcnt lgkmcnt(8)" ::: "memory"); SBAR(); PV_MM2(o[2], c); SBAR();
;   asm volatile("s_waitcnt lgkmcnt(0)" ::: "memory"); SBAR(); PV_MM2(o[3], d);
; }
	v_mfma_f32_32x32x16_bf16 v[16:31], v[64:67], v[108:111], v[16:31]
	v_exp_f32_e32 v201, v88
	v_exp_f32_e32 v203, v89
	v_exp_f32_e32 v205, v90
	v_exp_f32_e32 v217, v91
	v_exp_f32_e32 v197, v72
	v_exp_f32_e32 v193, v73
	v_exp_f32_e32 v195, v74
	v_mfma_f32_32x32x16_bf16 v[16:31], v[80:83], v[96:99], v[16:31]
	v_exp_f32_e32 v209, v75
	v_mfma_f32_32x32x16_bf16 v[16:31], v[104:107], v[100:103], v[16:31]
	v_mfma_f32_32x32x16_bf16 v[16:31], v[112:115], v[116:119], v[16:31]
	s_waitcnt lgkmcnt(0)
	v_mov_b32_e32 v149, v161
	v_add_f32_e64 v64, v170, v148
	v_add_f32_e64 v65, v171, v149
	v_mfma_f32_32x32x16_bf16 v[0:15], v[68:71], v[108:111], v[0:15]
	v_add_f32_e64 v64, v172, v64
	v_add_f32_e64 v65, v173, v65
	v_exp_f32_e32 v219, v92
	v_pk_add_f32 v[64:65], v[174:175], v[64:65]
	v_exp_f32_e32 v221, v93
	v_pk_add_f32 v[64:65], v[184:185], v[64:65]
	v_exp_f32_e32 v223, v94
	v_pk_add_f32 v[64:65], v[186:187], v[64:65]
	v_exp_f32_e32 v169, v95
	v_pk_add_f32 v[64:65], v[188:189], v[64:65]
	v_mfma_f32_32x32x16_bf16 v[0:15], v[84:87], v[96:99], v[0:15]
	v_add_f32_e64 v64, v190, v64
	v_add_f32_e64 v65, v191, v65
	v_exp_f32_e32 v211, v76
	v_pk_add_f32 v[64:65], v[206:207], v[64:65]
	v_exp_f32_e32 v213, v77
	v_pk_add_f32 v[64:65], v[200:201], v[64:65]
	v_exp_f32_e32 v215, v78
	v_pk_add_f32 v[64:65], v[202:203], v[64:65]
	v_mfma_f32_32x32x16_bf16 v[0:15], v[120:123], v[100:103], v[0:15]
	v_add_f32_e64 v64, v204, v64
	v_add_f32_e64 v65, v205, v65
	v_exp_f32_e32 v147, v79
	v_pk_add_f32 v[64:65], v[216:217], v[64:65]
	v_cvt_pk_bf16_f32 v66, v187, v189
	v_pk_add_f32 v[64:65], v[218:219], v[64:65]
	v_cvt_pk_bf16_f32 v67, v191, v207
	v_pk_add_f32 v[64:65], v[220:221], v[64:65]
	v_mfma_f32_32x32x16_bf16 v[0:15], v[124:127], v[116:119], v[0:15]
	v_add_f32_e64 v64, v222, v64
	v_add_f32_e64 v65, v223, v65
	v_cvt_pk_bf16_f32 v68, v201, v203
	v_add_f32_e64 v64, v168, v64
	v_add_f32_e64 v65, v169, v65
	v_cvt_pk_bf16_f32 v69, v205, v217
	v_pk_add_f32 v[64:65], v[156:157], v[64:65]
	v_cvt_pk_bf16_f32 v70, v219, v221
	v_pk_add_f32 v[64:65], v[158:159], v[64:65]
	v_cvt_pk_bf16_f32 v71, v223, v169
	v_pk_add_f32 v[64:65], v[166:167], v[64:65]
	v_cvt_pk_bf16_f32 v72, v157, v159
	v_pk_add_f32 v[64:65], v[176:177], v[64:65]
	v_cvt_pk_bf16_f32 v73, v167, v177
	v_pk_add_f32 v[64:65], v[178:179], v[64:65]
	v_cvt_pk_bf16_f32 v74, v179, v181
	v_pk_add_f32 v[64:65], v[180:181], v[64:65]
	v_cvt_pk_bf16_f32 v75, v183, v199
	v_pk_add_f32 v[64:65], v[182:183], v[64:65]
	v_cvt_pk_bf16_f32 v76, v197, v193
	v_pk_add_f32 v[64:65], v[198:199], v[64:65]
	v_cvt_pk_bf16_f32 v77, v195, v209
	v_pk_add_f32 v[64:65], v[196:197], v[64:65]
	v_cvt_pk_bf16_f32 v78, v211, v213
	v_pk_add_f32 v[64:65], v[192:193], v[64:65]
	v_cvt_pk_bf16_f32 v79, v215, v147
	v_pk_add_f32 v[64:65], v[194:195], v[64:65]
	s_nop 0
	v_pk_add_f32 v[64:65], v[208:209], v[64:65]
	s_nop 0
	v_pk_add_f32 v[64:65], v[210:211], v[64:65]
	s_nop 0
	v_pk_add_f32 v[64:65], v[212:213], v[64:65]
	s_nop 0
	v_pk_add_f32 v[64:65], v[214:215], v[64:65]
	s_nop 0
	v_pk_add_f32 v[64:65], v[146:147], v[64:65]
	s_nop 0
	v_pk_add_f32 v[112:113], v[64:65], v[64:65] op_sel:[0,1] op_sel_hi:[1,0]
	v_cvt_pk_bf16_f32 v64, v171, v173
	v_cvt_pk_bf16_f32 v65, v175, v185
	s_waitcnt vmcnt(0)
	s_barrier
	v_lshlrev_b32_e32 v222, 2, v245
	v_lshl_add_u32 v222, v160, 10, v222
	v_ashrrev_i32_e32 v223, 31, v222
	v_lshlrev_b64 v[222:223], 1, v[222:223]
	v_lshl_add_u64 v[220:221], s[40:41], 0, v[222:223]
	global_load_dwordx2 v[162:163], v[220:221], off
	global_load_dwordx2 v[164:165], v[220:221], off offset:16
	global_load_dwordx2 v[166:167], v[220:221], off offset:32
	global_load_dwordx2 v[168:169], v[220:221], off offset:48
	global_load_dwordx2 v[170:171], v[220:221], off offset:64
	global_load_dwordx2 v[172:173], v[220:221], off offset:80
	global_load_dwordx2 v[174:175], v[220:221], off offset:96
	global_load_dwordx2 v[176:177], v[220:221], off offset:112
	global_load_dwordx2 v[178:179], v[220:221], off offset:128
	global_load_dwordx2 v[180:181], v[220:221], off offset:144
	global_load_dwordx2 v[182:183], v[220:221], off offset:160
	global_load_dwordx2 v[184:185], v[220:221], off offset:176
	global_load_dwordx2 v[186:187], v[220:221], off offset:192
	global_load_dwordx2 v[188:189], v[220:221], off offset:208
	global_load_dwordx2 v[190:191], v[220:221], off offset:224
	global_load_dwordx2 v[192:193], v[220:221], off offset:240
	ds_read_b64_tr_b16 v[80:81], v246 offset:0
	ds_read_b64_tr_b16 v[82:83], v246 offset:0x100
	ds_read_b64_tr_b16 v[84:85], v246 offset:0x1000
	ds_read_b64_tr_b16 v[86:87], v246 offset:0x1100
	ds_read_b64_tr_b16 v[88:89], v246 offset:0x2000
	ds_read_b64_tr_b16 v[90:91], v246 offset:0x2100
	ds_read_b64_tr_b16 v[92:93], v246 offset:0x3000
	ds_read_b64_tr_b16 v[94:95], v246 offset:0x3100
	ds_read_b64_tr_b16 v[96:97], v246 offset:0x200
	ds_read_b64_tr_b16 v[98:99], v246 offset:0x300
	ds_read_b64_tr_b16 v[100:101], v246 offset:0x1200
	ds_read_b64_tr_b16 v[102:103], v246 offset:0x1300
	ds_read_b64_tr_b16 v[104:105], v246 offset:0x2200
	ds_read_b64_tr_b16 v[106:107], v246 offset:0x2300
	ds_read_b64_tr_b16 v[108:109], v246 offset:0x3200
	ds_read_b64_tr_b16 v[110:111], v246 offset:0x3300
	s_waitcnt lgkmcnt(8)
	s_nop 1
	v_mfma_f32_32x32x16_bf16 v[48:63], v[80:83], v[64:67], v[48:63]
	v_mfma_f32_32x32x16_bf16 v[48:63], v[84:87], v[68:71], v[48:63]
	v_mfma_f32_32x32x16_bf16 v[48:63], v[88:91], v[72:75], v[48:63]
	v_mfma_f32_32x32x16_bf16 v[48:63], v[92:95], v[76:79], v[48:63]
	ds_read_b64_tr_b16 v[80:81], v246 offset:0x400
	ds_read_b64_tr_b16 v[82:83], v246 offset:0x500
	ds_read_b64_tr_b16 v[84:85], v246 offset:0x1400
	ds_read_b64_tr_b16 v[86:87], v246 offset:0x1500
	ds_read_b64_tr_b16 v[88:89], v246 offset:0x2400
	ds_read_b64_tr_b16 v[90:91], v246 offset:0x2500
	ds_read_b64_tr_b16 v[92:93], v246 offset:0x3400
	ds_read_b64_tr_b16 v[94:95], v246 offset:0x3500
	s_waitcnt lgkmcnt(8)
; #define SBAR() __builtin_amdgcn_sched_barrier(0)
; #define PV_RD2(D0, X) const s16x4 X##l0 = tr_read<v_rd_off2(D0, 0, 0)>(vb), X##h0 = tr_read<v_rd_off2(D0, 0, 1)>(vb), X##l1 = tr_read<v_rd_off2(D0, 1, 0)>(vb), X##h1 = tr_read<v_rd_off2(D0, 1, 1)>(vb), \
;                               X##l2 = tr_read<v_rd_off2(D0, 2, 0)>(vb), X##h2 = tr_read<v_rd_off2(D0, 2, 1)>(vb), X##l3 = tr_read<v_rd_off2(D0, 3, 0)>(vb), X##h3 = tr_read<v_rd_off2(D0, 3, 1)>(vb)
; __device__ __forceinline__ void pv_d02(f32x16* o, int vb, bf16x8 pa0, bf16x8 pa1, bf16x8 pa2, bf16x8 pa3) {
;   PV_RD2(0, a);
;   PV_RD2(1, b); asm volatile("s_waitcnt lgkmcnt(8)" ::: "memory"); SBAR(); PV_MM2(o[0], a); SBAR();
;   PV_RD2(2, c); asm volatile("s_waitcnt lgkmcnt(8)" ::: "memory"); SBAR(); PV_MM2(o[1], b); SBAR();
;   PV_RD2(3, d); asm volatile("s_waitcnt lgkmcnt(8)" ::: "memory"); SBAR(); PV_MM2(o[2], c); SBAR();
;   asm volatile("s_waitcnt lgkmcnt(0)" ::: "memory"); SBAR(); PV_MM2(o[3], d);
; }
; __device__ __forceinline__ void attn_dense_body(const bf16* Qb, const bf16* __restrict__ Kh, const bf16* __restrict__ Vh, const bf16* __restrict__ Zb, ...
;     ...
;   { auto rr = __builtin_amdgcn_permlane32_swap(__float_as_uint(l_reg), __float_as_uint(l_reg), false, false); l_reg = __uint_as_float(rr[0]) + __uint_as_float(rr[1]); }
;   const float rl = __builtin_amdgcn_rcpf(l_reg);
;   { int lb = (wid * QBLK + r32) * LDO + 4 * hi; asm volatile("" : "+v"(lb));
	v_mfma_f32_32x32x16_bf16 v[32:47], v[96:99], v[64:67], v[32:47]
	v_mfma_f32_32x32x16_bf16 v[32:47], v[100:103], v[68:71], v[32:47]
	v_mfma_f32_32x32x16_bf16 v[32:47], v[104:107], v[72:75], v[32:47]
	v_mfma_f32_32x32x16_bf16 v[32:47], v[108:111], v[76:79], v[32:47]
	ds_read_b64_tr_b16 v[96:97], v246 offset:0x600
	ds_read_b64_tr_b16 v[98:99], v246 offset:0x700
	ds_read_b64_tr_b16 v[100:101], v246 offset:0x1600
	ds_read_b64_tr_b16 v[102:103], v246 offset:0x1700
	ds_read_b64_tr_b16 v[104:105], v246 offset:0x2600
	ds_read_b64_tr_b16 v[106:107], v246 offset:0x2700
	ds_read_b64_tr_b16 v[108:109], v246 offset:0x3600
	ds_read_b64_tr_b16 v[110:111], v246 offset:0x3700
	s_waitcnt lgkmcnt(8)
	v_mfma_f32_32x32x16_bf16 v[16:31], v[80:83], v[64:67], v[16:31]
	v_mfma_f32_32x32x16_bf16 v[16:31], v[84:87], v[68:71], v[16:31]
	v_mfma_f32_32x32x16_bf16 v[16:31], v[88:91], v[72:75], v[16:31]
	v_mfma_f32_32x32x16_bf16 v[16:31], v[92:95], v[76:79], v[16:31]
	s_waitcnt lgkmcnt(0)
	v_mfma_f32_32x32x16_bf16 v[0:15], v[96:99], v[64:67], v[0:15]
	v_mov_b32_e32 v64, v112
	s_nop 1
	v_permlane32_swap_b32_e32 v112, v64
	v_add_f32_e32 v64, v112, v64
	s_add_i32 s51, s51, s62
	s_cmp_ge_i32 s51, s6
	v_mfma_f32_32x32x16_bf16 v[0:15], v[100:103], v[68:71], v[0:15]
	v_rcp_f32_e32 v68, v64
	v_lshlrev_b32_e32 v64, 2, v245
	v_lshl_add_u32 v64, v160, 10, v64
	v_ashrrev_i32_e32 v65, 31, v64
	v_lshlrev_b64 v[66:67], 1, v[64:65]
	v_lshl_add_u64 v[64:65], s[24:25], 0, v[66:67]
	v_mfma_f32_32x32x16_bf16 v[0:15], v[104:107], v[72:75], v[0:15]
	v_mfma_f32_32x32x16_bf16 v[0:15], v[108:111], v[76:79], v[0:15]
	v_mul_f32_e32 v48, v48, v68
	v_mul_f32_e32 v49, v49, v68
	v_mul_f32_e32 v50, v50, v68
	v_mul_f32_e32 v51, v51, v68
	v_mul_f32_e32 v52, v52, v68
	v_mul_f32_e32 v53, v53, v68
	v_mul_f32_e32 v54, v54, v68
	v_mul_f32_e32 v55, v55, v68
	v_mul_f32_e32 v56, v56, v68
	v_mul_f32_e32 v57, v57, v68
	v_mul_f32_e32 v58, v58, v68
	v_mul_f32_e32 v59, v59, v68
	v_mul_f32_e32 v60, v60, v68
	v_mul_f32_e32 v61, v61, v68
	v_mul_f32_e32 v62, v62, v68
	v_mul_f32_e32 v63, v63, v68
	v_mul_f32_e32 v32, v32, v68
	v_mul_f32_e32 v33, v33, v68
	v_mul_f32_e32 v34, v34, v68
	v_mul_f32_e32 v35, v35, v68
	v_mul_f32_e32 v36, v36, v68
	v_mul_f32_e32 v37, v37, v68
	v_mul_f32_e32 v38, v38, v68
	v_mul_f32_e32 v39, v39, v68
	v_mul_f32_e32 v40, v40, v68
	v_mul_f32_e32 v41, v41, v68
	v_mul_f32_e32 v42, v42, v68
	v_mul_f32_e32 v43, v43, v68
	v_mul_f32_e32 v44, v44, v68
	v_mul_f32_e32 v45, v45, v68
	v_mul_f32_e32 v46, v46, v68
	v_mul_f32_e32 v47, v47, v68
	v_mul_f32_e32 v16, v16, v68
	v_mul_f32_e32 v17, v17, v68
	v_mul_f32_e32 v18, v18, v68
	v_mul_f32_e32 v19, v19, v68
	v_mul_f32_e32 v20, v20, v68
	v_mul_f32_e32 v21, v21, v68
	v_mul_f32_e32 v22, v22, v68
	v_mul_f32_e32 v23, v23, v68
	v_mul_f32_e32 v24, v24, v68
	v_mul_f32_e32 v25, v25, v68
	v_mul_f32_e32 v26, v26, v68
	v_mul_f32_e32 v27, v27, v68
	v_mul_f32_e32 v28, v28, v68
	v_mul_f32_e32 v29, v29, v68
	v_mul_f32_e32 v30, v30, v68
	v_mul_f32_e32 v31, v31, v68
	v_mul_f32_e32 v0, v0, v68
	v_mul_f32_e32 v1, v1, v68
	v_mul_f32_e32 v2, v2, v68
	v_mul_f32_e32 v3, v3, v68
	v_mul_f32_e32 v4, v4, v68
	v_mul_f32_e32 v5, v5, v68
	v_mul_f32_e32 v6, v6, v68
	v_mul_f32_e32 v7, v7, v68
	v_mul_f32_e32 v8, v8, v68
	v_mul_f32_e32 v9, v9, v68
	v_mul_f32_e32 v10, v10, v68
	v_mul_f32_e32 v11, v11, v68
	v_mul_f32_e32 v12, v12, v68
	v_mul_f32_e32 v13, v13, v68
	v_mul_f32_e32 v14, v14, v68
	v_mul_f32_e32 v15, v15, v68
	s_waitcnt vmcnt(0)
; __device__ __forceinline__ unsigned cvtpk(float lo, float hi) { return pg8::cvt_pk_bf16(lo, hi); }
; __device__ __forceinline__ void attn_dense_body(const bf16* Qb, const bf16* __restrict__ Kh, const bf16* __restrict__ Vh, const bf16* __restrict__ Zb, ...
;     ...
;   { int lb = (wid * QBLK + r32) * LDO + 4 * hi; asm volatile("" : "+v"(lb));
;     unsigned short* Ow = (unsigned short*)Ob + lb; const unsigned short* Zw = (const unsigned short*)Zb + lb;
; #pragma unroll
;     for (int d0 = 0; d0 < 4; ++d0)
; #pragma unroll
;       for (int g = 0; g < 4; ++g) { const int co = d0 * 32 + 8 * g; const unsigned long long zz = *(const unsigned long long*)(Zw + co);
;         const float z0 = __uint_as_float((unsigned)(zz << 16)), z1 = __uint_as_float((unsigned)zz & 0xffff0000u), z2 = __uint_as_float((unsigned)(zz >> 32) << 16), z3 = __uint_as_float((unsigned)(zz >> 32) & 0xffff0000u);
;         const unsigned w0 = cvtpk(o[d0][4 * g + 0] * rl * z0, o[d0][4 * g + 1] * rl * z1), w1 = cvtpk(o[d0][4 * g + 2] * rl * z2, o[d0][4 * g + 3] * rl * z3);
;         *(unsigned long long*)(Ow + co) = (unsigned long long)w0 | ((unsigned long long)w1 << 32); } }
	v_lshlrev_b32_e32 v194, 16, v162
	v_and_b32_e32 v195, 0xffff0000, v162
	v_lshlrev_b32_e32 v196, 16, v163
	v_and_b32_e32 v197, 0xffff0000, v163
	v_mul_f32_e32 v48, v48, v194
	v_mul_f32_e32 v49, v49, v195
	v_mul_f32_e32 v50, v50, v196
	v_mul_f32_e32 v51, v51, v197
	v_cvt_pk_bf16_f32 v48, v48, v49
	v_cvt_pk_bf16_f32 v49, v50, v51
	global_store_dwordx2 v[64:65], v[48:49], off
	v_lshlrev_b32_e32 v194, 16, v164
	v_and_b32_e32 v195, 0xffff0000, v164
	v_lshlrev_b32_e32 v196, 16, v165
	v_and_b32_e32 v197, 0xffff0000, v165
	v_mul_f32_e32 v52, v52, v194
	v_mul_f32_e32 v53, v53, v195
	v_mul_f32_e32 v54, v54, v196
	v_mul_f32_e32 v55, v55, v197
	v_cvt_pk_bf16_f32 v52, v52, v53
	v_cvt_pk_bf16_f32 v53, v54, v55
	global_store_dwordx2 v[64:65], v[52:53], off offset:16
	v_lshlrev_b32_e32 v194, 16, v166
	v_and_b32_e32 v195, 0xffff0000, v166
	v_lshlrev_b32_e32 v196, 16, v167
	v_and_b32_e32 v197, 0xffff0000, v167
	v_mul_f32_e32 v56, v56, v194
	v_mul_f32_e32 v57, v57, v195
	v_mul_f32_e32 v58, v58, v196
	v_mul_f32_e32 v59, v59, v197
	v_cvt_pk_bf16_f32 v56, v56, v57
	v_cvt_pk_bf16_f32 v57, v58, v59
	global_store_dwordx2 v[64:65], v[56:57], off offset:32
	v_lshlrev_b32_e32 v194, 16, v168
	v_and_b32_e32 v195, 0xffff0000, v168
	v_lshlrev_b32_e32 v196, 16, v169
	v_and_b32_e32 v197, 0xffff0000, v169
	v_mul_f32_e32 v60, v60, v194
	v_mul_f32_e32 v61, v61, v195
	v_mul_f32_e32 v62, v62, v196
	v_mul_f32_e32 v63, v63, v197
	v_cvt_pk_bf16_f32 v60, v60, v61
	v_cvt_pk_bf16_f32 v61, v62, v63
	global_store_dwordx2 v[64:65], v[60:61], off offset:48
	v_lshlrev_b32_e32 v194, 16, v170
	v_and_b32_e32 v195, 0xffff0000, v170
	v_lshlrev_b32_e32 v196, 16, v171
	v_and_b32_e32 v197, 0xffff0000, v171
	v_mul_f32_e32 v32, v32, v194
	v_mul_f32_e32 v33, v33, v195
	v_mul_f32_e32 v34, v34, v196
	v_mul_f32_e32 v35, v35, v197
	v_cvt_pk_bf16_f32 v32, v32, v33
	v_cvt_pk_bf16_f32 v33, v34, v35
	global_store_dwordx2 v[64:65], v[32:33], off offset:64
	v_lshlrev_b32_e32 v194, 16, v172
	v_and_b32_e32 v195, 0xffff0000, v172
	v_lshlrev_b32_e32 v196, 16, v173
	v_and_b32_e32 v197, 0xffff0000, v173
	v_mul_f32_e32 v36, v36, v194
	v_mul_f32_e32 v37, v37, v195
	v_mul_f32_e32 v38, v38, v196
	v_mul_f32_e32 v39, v39, v197
	v_cvt_pk_bf16_f32 v36, v36, v37
	v_cvt_pk_bf16_f32 v37, v38, v39
	global_store_dwordx2 v[64:65], v[36:37], off offset:80
	v_lshlrev_b32_e32 v194, 16, v174
	v_and_b32_e32 v195, 0xffff0000, v174
	v_lshlrev_b32_e32 v196, 16, v175
	v_and_b32_e32 v197, 0xffff0000, v175
	v_mul_f32_e32 v40, v40, v194
	v_mul_f32_e32 v41, v41, v195
	v_mul_f32_e32 v42, v42, v196
	v_mul_f32_e32 v43, v43, v197
	v_cvt_pk_bf16_f32 v40, v40, v41
	v_cvt_pk_bf16_f32 v41, v42, v43
	global_store_dwordx2 v[64:65], v[40:41], off offset:96
	v_lshlrev_b32_e32 v194, 16, v176
	v_and_b32_e32 v195, 0xffff0000, v176
	v_lshlrev_b32_e32 v196, 16, v177
	v_and_b32_e32 v197, 0xffff0000, v177
	v_mul_f32_e32 v44, v44, v194
	v_mul_f32_e32 v45, v45, v195
	v_mul_f32_e32 v46, v46, v196
	v_mul_f32_e32 v47, v47, v197
	v_cvt_pk_bf16_f32 v44, v44, v45
	v_cvt_pk_bf16_f32 v45, v46, v47
	global_store_dwordx2 v[64:65], v[44:45], off offset:112
	v_lshlrev_b32_e32 v194, 16, v178
	v_and_b32_e32 v195, 0xffff0000, v178
	v_lshlrev_b32_e32 v196, 16, v179
	v_and_b32_e32 v197, 0xffff0000, v179
	v_mul_f32_e32 v16, v16, v194
	v_mul_f32_e32 v17, v17, v195
	v_mul_f32_e32 v18, v18, v196
	v_mul_f32_e32 v19, v19, v197
	v_cvt_pk_bf16_f32 v16, v16, v17
	v_cvt_pk_bf16_f32 v17, v18, v19
	global_store_dwordx2 v[64:65], v[16:17], off offset:128
	v_lshlrev_b32_e32 v194, 16, v180
	v_and_b32_e32 v195, 0xffff0000, v180
	v_lshlrev_b32_e32 v196, 16, v181
	v_and_b32_e32 v197, 0xffff0000, v181
	v_mul_f32_e32 v20, v20, v194
	v_mul_f32_e32 v21, v21, v195
	v_mul_f32_e32 v22, v22, v196
	v_mul_f32_e32 v23, v23, v197
	v_cvt_pk_bf16_f32 v20, v20, v21
	v_cvt_pk_bf16_f32 v21, v22, v23
	global_store_dwordx2 v[64:65], v[20:21], off offset:144
	v_lshlrev_b32_e32 v194, 16, v182
	v_and_b32_e32 v195, 0xffff0000, v182
	v_lshlrev_b32_e32 v196, 16, v183
	v_and_b32_e32 v197, 0xffff0000, v183
	v_mul_f32_e32 v24, v24, v194
	v_mul_f32_e32 v25, v25, v195
	v_mul_f32_e32 v26, v26, v196
	v_mul_f32_e32 v27, v27, v197
	v_cvt_pk_bf16_f32 v24, v24, v25
	v_cvt_pk_bf16_f32 v25, v26, v27
	global_store_dwordx2 v[64:65], v[24:25], off offset:160
	v_lshlrev_b32_e32 v194, 16, v184
	v_and_b32_e32 v195, 0xffff0000, v184
	v_lshlrev_b32_e32 v196, 16, v185
	v_and_b32_e32 v197, 0xffff0000, v185
	v_mul_f32_e32 v28, v28, v194
	v_mul_f32_e32 v29, v29, v195
	v_mul_f32_e32 v30, v30, v196
	v_mul_f32_e32 v31, v31, v197
	v_cvt_pk_bf16_f32 v28, v28, v29
	v_cvt_pk_bf16_f32 v29, v30, v31
	global_store_dwordx2 v[64:65], v[28:29], off offset:176
	v_lshlrev_b32_e32 v194, 16, v186
	v_and_b32_e32 v195, 0xffff0000, v186
	v_lshlrev_b32_e32 v196, 16, v187
	v_and_b32_e32 v197, 0xffff0000, v187
	v_mul_f32_e32 v0, v0, v194
	v_mul_f32_e32 v1, v1, v195
	v_mul_f32_e32 v2, v2, v196
	v_mul_f32_e32 v3, v3, v197
	v_cvt_pk_bf16_f32 v0, v0, v1
	v_cvt_pk_bf16_f32 v1, v2, v3
	global_store_dwordx2 v[64:65], v[0:1], off offset:192
	v_lshlrev_b32_e32 v194, 16, v188
	v_and_b32_e32 v195, 0xffff0000, v188
	v_lshlrev_b32_e32 v196, 16, v189
	v_and_b32_e32 v197, 0xffff0000, v189
	v_mul_f32_e32 v4, v4, v194
	v_mul_f32_e32 v5, v5, v195
	v_mul_f32_e32 v6, v6, v196
	v_mul_f32_e32 v7, v7, v197
	v_cvt_pk_bf16_f32 v4, v4, v5
	v_cvt_pk_bf16_f32 v5, v6, v7
	global_store_dwordx2 v[64:65], v[4:5], off offset:208
	v_lshlrev_b32_e32 v194, 16, v190
	v_and_b32_e32 v195, 0xffff0000, v190
	v_lshlrev_b32_e32 v196, 16, v191
	v_and_b32_e32 v197, 0xffff0000, v191
	v_mul_f32_e32 v8, v8, v194
	v_mul_f32_e32 v9, v9, v195
	v_mul_f32_e32 v10, v10, v196
	v_mul_f32_e32 v11, v11, v197
	v_cvt_pk_bf16_f32 v8, v8, v9
	v_cvt_pk_bf16_f32 v9, v10, v11
	global_store_dwordx2 v[64:65], v[8:9], off offset:224
	v_lshlrev_b32_e32 v194, 16, v192
	v_and_b32_e32 v195, 0xffff0000, v192
	v_lshlrev_b32_e32 v196, 16, v193
	v_and_b32_e32 v197, 0xffff0000, v193
	v_mul_f32_e32 v12, v12, v194
	v_mul_f32_e32 v13, v13, v195
	v_mul_f32_e32 v14, v14, v196
	v_mul_f32_e32 v15, v15, v197
	v_cvt_pk_bf16_f32 v12, v12, v13
	v_cvt_pk_bf16_f32 v13, v14, v15
	global_store_dwordx2 v[64:65], v[12:13], off offset:240
	s_cbranch_scc0 .LBB0_112
	v_readlane_b32 s84, v255, 16
	v_readlane_b32 s85, v255, 17
	v_readlane_b32 s86, v255, 18
	v_readlane_b32 s87, v255, 19
	s_nop 3
